# sample attention LDS-DMA: rows 1-3 and 5-7 of a wave's 8 rows use the instruction offset (applied to both the memory and the LDS address) instead of re-forming m0 and the address
# speedup vs baseline: 1.0058x; 1.0058x over previous
.LBB0_803:
	v_lshrrev_b32_e32 v45, 4, v43
	v_lshlrev_b32_e32 v34, 2, v43
	v_and_b32_e32 v34, 12, v34
	v_bfe_u32 v35, v43, 2, 2
	v_add_u32_e32 v38, 8, v45
	v_add_u32_e32 v37, 4, v45
	v_bitop3_b32 v47, v34, v38, v35 bitop3:0x36
	v_add_u32_e32 v38, 12, v45
	s_cmp_eq_u32 s10, 64
	v_bitop3_b32 v36, v34, v45, v35 bitop3:0x36
	v_bitop3_b32 v37, v34, v37, v35 bitop3:0x36
	v_bitop3_b32 v46, v34, v38, v35 bitop3:0x36
	v_lshl_add_u64 v[34:35], v[192:193], 0, s[24:25]
	s_cselect_b64 s[22:23], -1, 0
	v_lshlrev_b64 v[34:35], 7, v[34:35]
	s_add_u32 s10, s15, s24
	v_lshl_add_u64 v[38:39], v[196:197], 0, v[34:35]
	s_addc_u32 s11, s17, s25
	v_lshlrev_b32_e32 v34, 8, v43
	s_lshl_b64 s[10:11], s[10:11], 10
	v_and_b32_e32 v34, 0xf00, v34
	v_lshrrev_b32_e32 v44, 2, v43
	v_lshl_add_u64 v[40:41], v[212:213], 0, s[10:11]
	v_lshl_add_u32 v46, v46, 4, v34
	v_lshl_add_u32 v47, v47, 4, v34
	v_lshl_add_u32 v48, v37, 4, v34
	v_lshl_add_u32 v49, v36, 4, v34
	s_and_b64 vcc, exec, s[20:21]
	s_mov_b64 s[24:25], 0x1000
	v_add_u32_e32 v207, 0xb800, v219
	v_add_u32_e32 v208, v219, v216
	ds_read_b128 v[34:37], v49
	ds_read_b128 v[182:185], v48
	ds_read_b128 v[186:189], v47
	ds_read_b128 v[202:205], v46
	s_waitcnt lgkmcnt(2)
	v_mfma_f32_16x16x32_bf16 v[226:229], v[50:53], v[34:37], 0
	v_mfma_f32_16x16x32_bf16 v[230:233], v[82:85], v[34:37], 0
	v_mfma_f32_16x16x32_bf16 v[234:237], v[114:117], v[34:37], 0
	v_mfma_f32_16x16x32_bf16 v[238:241], v[146:149], v[34:37], 0
	s_cbranch_vccz .Lsa_nd0
	s_add_i32 m0, s35, 0xf400
	s_nop 0
	global_load_lds_dwordx4 v[40:41], off nt
.Lsa_nd0:
	v_mfma_f32_16x16x32_bf16 v[226:229], v[54:57], v[182:185], v[226:229]
	v_mfma_f32_16x16x32_bf16 v[230:233], v[86:89], v[182:185], v[230:233]
	v_mfma_f32_16x16x32_bf16 v[234:237], v[118:121], v[182:185], v[234:237]
	v_mfma_f32_16x16x32_bf16 v[238:241], v[150:153], v[182:185], v[238:241]
	s_cbranch_vccz .Lsa_nd1
	global_load_lds_dwordx4 v[40:41], off offset:1024 nt
.Lsa_nd1:
	ds_read_b128 v[34:37], v49 offset:16384
	ds_read_b128 v[182:185], v48 offset:16384
	s_waitcnt lgkmcnt(2)
	v_mfma_f32_16x16x32_bf16 v[226:229], v[58:61], v[186:189], v[226:229]
	v_mfma_f32_16x16x32_bf16 v[230:233], v[90:93], v[186:189], v[230:233]
	v_mfma_f32_16x16x32_bf16 v[234:237], v[122:125], v[186:189], v[234:237]
	v_mfma_f32_16x16x32_bf16 v[238:241], v[154:157], v[186:189], v[238:241]
	s_cbranch_vccz .Lsa_nd2
	global_load_lds_dwordx4 v[40:41], off offset:2048 nt
.Lsa_nd2:
	v_mfma_f32_16x16x32_bf16 v[226:229], v[62:65], v[202:205], v[226:229]
	v_mfma_f32_16x16x32_bf16 v[230:233], v[94:97], v[202:205], v[230:233]
	v_mfma_f32_16x16x32_bf16 v[234:237], v[126:129], v[202:205], v[234:237]
	v_mfma_f32_16x16x32_bf16 v[238:241], v[158:161], v[202:205], v[238:241]
	s_cbranch_vccz .Lsa_nd3
	global_load_lds_dwordx4 v[40:41], off offset:3072 nt
.Lsa_nd3:
	ds_read_b128 v[186:189], v47 offset:16384
	ds_read_b128 v[202:205], v46 offset:16384
	s_waitcnt lgkmcnt(2)
	v_mfma_f32_16x16x32_bf16 v[226:229], v[66:69], v[34:37], v[226:229]
	v_mfma_f32_16x16x32_bf16 v[230:233], v[98:101], v[34:37], v[230:233]
	v_mfma_f32_16x16x32_bf16 v[234:237], v[130:133], v[34:37], v[234:237]
	v_mfma_f32_16x16x32_bf16 v[238:241], v[162:165], v[34:37], v[238:241]
	s_cbranch_vccz .Lsa_nd4
	v_lshl_add_u64 v[40:41], v[40:41], 0, s[24:25]
	s_add_i32 m0, s35, 0x10400
	s_nop 0
	global_load_lds_dwordx4 v[40:41], off nt
.Lsa_nd4:
	v_mfma_f32_16x16x32_bf16 v[226:229], v[70:73], v[182:185], v[226:229]
	v_mfma_f32_16x16x32_bf16 v[230:233], v[102:105], v[182:185], v[230:233]
	v_mfma_f32_16x16x32_bf16 v[234:237], v[134:137], v[182:185], v[234:237]
	v_mfma_f32_16x16x32_bf16 v[238:241], v[166:169], v[182:185], v[238:241]
	s_cbranch_vccz .Lsa_nd5
	global_load_lds_dwordx4 v[40:41], off offset:1024 nt
.Lsa_nd5:
	ds_read2_b64 v[34:37], v207 offset1:4
	ds_read2_b64 v[182:185], v207 offset0:8 offset1:12
	s_waitcnt lgkmcnt(2)
	v_mfma_f32_16x16x32_bf16 v[226:229], v[74:77], v[186:189], v[226:229]
	v_mfma_f32_16x16x32_bf16 v[230:233], v[106:109], v[186:189], v[230:233]
	v_mfma_f32_16x16x32_bf16 v[234:237], v[138:141], v[186:189], v[234:237]
	v_mfma_f32_16x16x32_bf16 v[238:241], v[170:173], v[186:189], v[238:241]
	s_cbranch_vccz .Lsa_nd6
	global_load_lds_dwordx4 v[40:41], off offset:2048 nt
.Lsa_nd6:
	v_mfma_f32_16x16x32_bf16 v[226:229], v[78:81], v[202:205], v[226:229]
	v_mfma_f32_16x16x32_bf16 v[230:233], v[110:113], v[202:205], v[230:233]
	v_mfma_f32_16x16x32_bf16 v[234:237], v[142:145], v[202:205], v[234:237]
	v_mfma_f32_16x16x32_bf16 v[238:241], v[174:177], v[202:205], v[238:241]
	ds_read_b128 v[186:189], v225 offset:0
	ds_read_b128 v[202:205], v208 offset:47232
	s_cbranch_vccz .Lsa_nd7
	global_load_lds_dwordx4 v[40:41], off offset:3072 nt
